# L0 out-projection epilogue: second group of each residual-load pair issued with the first (one exposed load latency per pair instead of two)
# speedup vs baseline: 1.0033x; 1.0033x over previous
.LBB0_495:
	s_lshl_b32 s6, s28, 8
	s_add_i32 s6, s6, s42
	v_or_b32_e32 v146, s6, v186
	v_cmp_lt_i32_e32 vcc, s48, v146
	s_and_saveexec_b64 s[28:29], vcc
	v_readlane_b32 s64, v251, 50
	v_readlane_b32 s36, v251, 2
	s_xor_b64 s[28:29], exec, s[28:29]
	v_readlane_b32 s69, v251, 49
	v_readlane_b32 s65, v251, 51
	v_readlane_b32 s37, v251, 3
	v_add_u32_e32 v132, 0xffffc000, v146
	v_lshlrev_b64 v[140:141], 12, v[132:133]
	v_lshl_add_u64 v[144:145], s[76:77], 0, v[140:141]
	v_mov_b32_e32 v147, v133
	s_or_saveexec_b64 s[30:31], s[28:29]
	s_ashr_i32 s7, s6, 11
	s_mul_i32 s28, s7, 0xc00
	v_mov_b64_e32 v[142:143], 0x6000
	s_xor_b64 exec, exec, s[30:31]
	v_ashrrev_i32_e32 v147, 31, v146
	v_lshlrev_b64 v[140:141], 12, v[146:147]
	s_ashr_i32 s29, s28, 31
	v_lshl_add_u64 v[144:145], s[72:73], 0, v[140:141]
	v_mov_b64_e32 v[142:143], s[28:29]
	s_or_b64 exec, exec, s[30:31]
	v_lshl_or_b32 v140, s24, 8, v153
	v_ashrrev_i32_e32 v141, 31, v140
	v_lshl_add_u64 v[142:143], v[142:143], 2, s[36:37]
	v_lshl_add_u64 v[182:183], v[142:143], 0, s[14:15]
	v_lshlrev_b64 v[142:143], 2, v[140:141]
	v_lshl_add_u64 v[184:185], v[144:145], 0, v[142:143]
	v_lshl_add_u64 v[144:145], v[182:183], 0, v[142:143]
	global_load_dwordx4 v[158:161], v[144:145], off
	global_load_dwordx4 v[170:173], v[184:185], off
	global_load_dwordx4 v[174:177], v[184:185], off offset:16
	global_load_dwordx4 v[178:181], v[144:145], off offset:16
	v_lshlrev_b64 v[144:145], 11, v[146:147]
	v_lshl_add_u64 v[188:189], s[26:27], 0, v[144:145]
	v_or_b32_e32 v144, 0x80, v140
	v_lshl_add_u64 v[188:189], v[140:141], 1, v[188:189]
	v_ashrrev_i32_e32 v145, 31, v144
	v_lshl_add_u64 v[182:183], v[144:145], 2, v[182:183]
	global_load_dwordx4 v[210:213], v[182:183], off
	global_load_dwordx4 v[214:217], v[184:185], off offset:512
	global_load_dwordx4 v[218:221], v[184:185], off offset:528
	global_load_dwordx4 v[222:225], v[182:183], off offset:16
	s_waitcnt vmcnt(4)
	v_pk_fma_f32 v[128:129], v[128:129], v[160:161], v[172:173]
	v_pk_fma_f32 v[126:127], v[126:127], v[158:159], v[170:171]
	v_pk_fma_f32 v[158:159], v[124:125], v[180:181], v[176:177]
	v_pk_fma_f32 v[124:125], v[122:123], v[178:179], v[174:175]
	v_cvt_pk_bf16_f32 v122, v126, v127
	v_cvt_pk_bf16_f32 v123, v128, v129
	v_cvt_pk_bf16_f32 v124, v124, v125
	v_cvt_pk_bf16_f32 v125, v158, v159
	global_store_dwordx4 v[188:189], v[122:125], off
	s_nop 0
	v_or_b32_e32 v122, 16, v146
	v_cmp_lt_i32_e32 vcc, s48, v122
	s_waitcnt vmcnt(3)
	v_pk_fma_f32 v[120:121], v[120:121], v[212:213], v[216:217]
	v_pk_fma_f32 v[118:119], v[118:119], v[210:211], v[214:215]
	s_waitcnt vmcnt(1)
	v_pk_fma_f32 v[124:125], v[116:117], v[224:225], v[220:221]
	v_pk_fma_f32 v[116:117], v[114:115], v[222:223], v[218:219]
	v_cvt_pk_bf16_f32 v114, v118, v119
	v_cvt_pk_bf16_f32 v115, v120, v121
	v_cvt_pk_bf16_f32 v116, v116, v117
	v_cvt_pk_bf16_f32 v117, v124, v125
	global_store_dwordx4 v[188:189], v[114:117], off offset:256
	s_and_saveexec_b64 s[24:25], vcc
	s_xor_b64 s[24:25], exec, s[24:25]
	v_add_u32_e32 v132, 0xffffc010, v146
	v_lshlrev_b64 v[114:115], 12, v[132:133]
	v_lshl_add_u64 v[114:115], s[76:77], 0, v[114:115]
	v_mov_b32_e32 v123, v133
	s_or_saveexec_b64 s[24:25], s[24:25]
	v_mov_b64_e32 v[116:117], 0x6000
	s_xor_b64 exec, exec, s[24:25]
	v_ashrrev_i32_e32 v123, 31, v122
	v_lshlrev_b64 v[114:115], 12, v[122:123]
	s_ashr_i32 s29, s28, 31
	v_lshl_add_u64 v[114:115], s[72:73], 0, v[114:115]
	v_mov_b64_e32 v[116:117], s[28:29]
	s_or_b64 exec, exec, s[24:25]
	v_lshl_add_u64 v[116:117], v[116:117], 2, s[36:37]
	v_lshl_add_u64 v[128:129], v[116:117], 0, s[14:15]
	v_lshl_add_u64 v[158:159], v[128:129], 0, v[142:143]
	v_lshl_add_u64 v[170:171], v[114:115], 0, v[142:143]
	global_load_dwordx4 v[114:117], v[158:159], off
	global_load_dwordx4 v[118:121], v[170:171], off
	global_load_dwordx4 v[124:127], v[170:171], off offset:16
	s_nop 0
	global_load_dwordx4 v[158:161], v[158:159], off offset:16
	v_lshlrev_b64 v[122:123], 11, v[122:123]
	v_lshl_add_u64 v[122:123], s[26:27], 0, v[122:123]
	v_lshl_add_u64 v[172:173], v[140:141], 1, v[122:123]
	v_lshl_add_u64 v[122:123], v[144:145], 2, v[128:129]
	global_load_dwordx4 v[210:213], v[122:123], off
	global_load_dwordx4 v[214:217], v[170:171], off offset:512
	global_load_dwordx4 v[218:221], v[170:171], off offset:528
	global_load_dwordx4 v[222:225], v[122:123], off offset:16
	s_waitcnt vmcnt(6)
	v_pk_fma_f32 v[112:113], v[112:113], v[116:117], v[120:121]
	v_pk_fma_f32 v[110:111], v[110:111], v[114:115], v[118:119]
	s_waitcnt vmcnt(4)
	v_pk_fma_f32 v[114:115], v[108:109], v[160:161], v[126:127]
	v_pk_fma_f32 v[108:109], v[106:107], v[158:159], v[124:125]
	v_cvt_pk_bf16_f32 v106, v110, v111
	v_cvt_pk_bf16_f32 v107, v112, v113
	v_cvt_pk_bf16_f32 v108, v108, v109
	v_cvt_pk_bf16_f32 v109, v114, v115
	global_store_dwordx4 v[172:173], v[106:109], off
	s_nop 0
	s_nop 0
	v_or_b32_e32 v106, 32, v146
	v_cmp_lt_i32_e32 vcc, s48, v106
	s_waitcnt vmcnt(3)
	v_pk_fma_f32 v[104:105], v[104:105], v[212:213], v[216:217]
	v_pk_fma_f32 v[102:103], v[102:103], v[210:211], v[214:215]
	s_waitcnt vmcnt(1)
	v_pk_fma_f32 v[108:109], v[100:101], v[224:225], v[220:221]
	v_pk_fma_f32 v[100:101], v[98:99], v[222:223], v[218:219]
	v_cvt_pk_bf16_f32 v98, v102, v103
	v_cvt_pk_bf16_f32 v99, v104, v105
	v_cvt_pk_bf16_f32 v100, v100, v101
	v_cvt_pk_bf16_f32 v101, v108, v109
	global_store_dwordx4 v[172:173], v[98:101], off offset:256
	s_and_saveexec_b64 s[24:25], vcc
	s_xor_b64 s[24:25], exec, s[24:25]
	v_add_u32_e32 v132, 0xffffc020, v146
	v_lshlrev_b64 v[98:99], 12, v[132:133]
	v_lshl_add_u64 v[98:99], s[76:77], 0, v[98:99]
	v_mov_b32_e32 v107, v133
	s_or_saveexec_b64 s[24:25], s[24:25]
	v_mov_b64_e32 v[100:101], 0x6000
	s_xor_b64 exec, exec, s[24:25]
	v_ashrrev_i32_e32 v107, 31, v106
	v_lshlrev_b64 v[98:99], 12, v[106:107]
	s_ashr_i32 s29, s28, 31
	v_lshl_add_u64 v[98:99], s[72:73], 0, v[98:99]
	v_mov_b64_e32 v[100:101], s[28:29]
	s_or_b64 exec, exec, s[24:25]
	v_lshl_add_u64 v[100:101], v[100:101], 2, s[36:37]
	v_lshl_add_u64 v[116:117], v[100:101], 0, s[14:15]
	v_lshl_add_u64 v[112:113], v[116:117], 0, v[142:143]
	v_lshl_add_u64 v[118:119], v[98:99], 0, v[142:143]
	global_load_dwordx4 v[98:101], v[112:113], off
	global_load_dwordx4 v[102:105], v[118:119], off
	global_load_dwordx4 v[108:111], v[118:119], off offset:16
	s_nop 0
	global_load_dwordx4 v[112:115], v[112:113], off offset:16
	v_lshlrev_b64 v[106:107], 11, v[106:107]
	v_lshl_add_u64 v[106:107], s[26:27], 0, v[106:107]
	v_lshl_add_u64 v[120:121], v[140:141], 1, v[106:107]
	v_lshl_add_u64 v[106:107], v[144:145], 2, v[116:117]
	global_load_dwordx4 v[210:213], v[106:107], off
	global_load_dwordx4 v[214:217], v[118:119], off offset:512
	global_load_dwordx4 v[218:221], v[118:119], off offset:528
	global_load_dwordx4 v[222:225], v[106:107], off offset:16
	s_waitcnt vmcnt(6)
	v_pk_fma_f32 v[96:97], v[96:97], v[100:101], v[104:105]
	v_pk_fma_f32 v[94:95], v[94:95], v[98:99], v[102:103]
	s_waitcnt vmcnt(4)
	v_pk_fma_f32 v[98:99], v[92:93], v[114:115], v[110:111]
	v_pk_fma_f32 v[92:93], v[90:91], v[112:113], v[108:109]
	v_cvt_pk_bf16_f32 v90, v94, v95
	v_cvt_pk_bf16_f32 v91, v96, v97
	v_cvt_pk_bf16_f32 v92, v92, v93
	v_cvt_pk_bf16_f32 v93, v98, v99
	global_store_dwordx4 v[120:121], v[90:93], off
	s_nop 0
	s_nop 0
	v_or_b32_e32 v90, 48, v146
	v_cmp_lt_i32_e32 vcc, s48, v90
	s_waitcnt vmcnt(3)
	v_pk_fma_f32 v[88:89], v[88:89], v[212:213], v[216:217]
	v_pk_fma_f32 v[86:87], v[86:87], v[210:211], v[214:215]
	s_waitcnt vmcnt(1)
	v_pk_fma_f32 v[92:93], v[84:85], v[224:225], v[220:221]
	v_pk_fma_f32 v[84:85], v[82:83], v[222:223], v[218:219]
	v_cvt_pk_bf16_f32 v82, v86, v87
	v_cvt_pk_bf16_f32 v83, v88, v89
	v_cvt_pk_bf16_f32 v84, v84, v85
	v_cvt_pk_bf16_f32 v85, v92, v93
	global_store_dwordx4 v[120:121], v[82:85], off offset:256
	s_and_saveexec_b64 s[24:25], vcc
	s_xor_b64 s[24:25], exec, s[24:25]
	v_add_u32_e32 v132, 0xffffc030, v146
	v_lshlrev_b64 v[82:83], 12, v[132:133]
	v_lshl_add_u64 v[82:83], s[76:77], 0, v[82:83]
	v_mov_b32_e32 v91, v133
	s_or_saveexec_b64 s[24:25], s[24:25]
	v_mov_b64_e32 v[84:85], 0x6000
	s_xor_b64 exec, exec, s[24:25]
	v_ashrrev_i32_e32 v91, 31, v90
	v_lshlrev_b64 v[82:83], 12, v[90:91]
	s_ashr_i32 s29, s28, 31
	v_lshl_add_u64 v[82:83], s[72:73], 0, v[82:83]
	v_mov_b64_e32 v[84:85], s[28:29]
	s_or_b64 exec, exec, s[24:25]
	v_lshl_add_u64 v[84:85], v[84:85], 2, s[36:37]
	v_lshl_add_u64 v[100:101], v[84:85], 0, s[14:15]
	v_lshl_add_u64 v[96:97], v[100:101], 0, v[142:143]
	v_lshl_add_u64 v[102:103], v[82:83], 0, v[142:143]
	global_load_dwordx4 v[82:85], v[96:97], off
	global_load_dwordx4 v[86:89], v[102:103], off
	global_load_dwordx4 v[92:95], v[102:103], off offset:16
	s_nop 0
	global_load_dwordx4 v[96:99], v[96:97], off offset:16
	v_lshlrev_b64 v[90:91], 11, v[90:91]
	v_lshl_add_u64 v[90:91], s[26:27], 0, v[90:91]
	v_lshl_add_u64 v[104:105], v[140:141], 1, v[90:91]
	v_lshl_add_u64 v[90:91], v[144:145], 2, v[100:101]
	s_add_i32 s17, s6, 0x80
	global_load_dwordx4 v[210:213], v[90:91], off
	global_load_dwordx4 v[214:217], v[102:103], off offset:512
	global_load_dwordx4 v[218:221], v[102:103], off offset:528
	global_load_dwordx4 v[222:225], v[90:91], off offset:16
	s_waitcnt vmcnt(6)
	v_pk_fma_f32 v[80:81], v[80:81], v[84:85], v[88:89]
	v_pk_fma_f32 v[78:79], v[78:79], v[82:83], v[86:87]
	s_waitcnt vmcnt(4)
	v_pk_fma_f32 v[82:83], v[76:77], v[98:99], v[94:95]
	v_pk_fma_f32 v[76:77], v[74:75], v[96:97], v[92:93]
	v_cvt_pk_bf16_f32 v74, v78, v79
	v_cvt_pk_bf16_f32 v75, v80, v81
	v_cvt_pk_bf16_f32 v76, v76, v77
	v_cvt_pk_bf16_f32 v77, v82, v83
	global_store_dwordx4 v[104:105], v[74:77], off
	s_nop 0
	s_nop 0
	v_or_b32_e32 v74, s17, v186
	v_cmp_lt_i32_e32 vcc, s48, v74
	s_waitcnt vmcnt(3)
	v_pk_fma_f32 v[72:73], v[72:73], v[212:213], v[216:217]
	v_pk_fma_f32 v[70:71], v[70:71], v[210:211], v[214:215]
	s_waitcnt vmcnt(1)
	v_pk_fma_f32 v[76:77], v[68:69], v[224:225], v[220:221]
	v_pk_fma_f32 v[68:69], v[66:67], v[222:223], v[218:219]
	v_cvt_pk_bf16_f32 v66, v70, v71
	v_cvt_pk_bf16_f32 v67, v72, v73
	v_cvt_pk_bf16_f32 v68, v68, v69
	v_cvt_pk_bf16_f32 v69, v76, v77
	global_store_dwordx4 v[104:105], v[66:69], off offset:256
	s_and_saveexec_b64 s[6:7], vcc
	s_xor_b64 s[6:7], exec, s[6:7]
	v_add_u32_e32 v132, 0xffffc000, v74
	v_lshlrev_b64 v[66:67], 12, v[132:133]
	v_lshl_add_u64 v[66:67], s[76:77], 0, v[66:67]
	v_mov_b32_e32 v75, v133
	s_or_saveexec_b64 s[28:29], s[6:7]
	s_ashr_i32 s6, s17, 11
	s_mul_i32 s24, s6, 0xc00
	v_mov_b64_e32 v[68:69], 0x6000
	s_xor_b64 exec, exec, s[28:29]
	v_ashrrev_i32_e32 v75, 31, v74
	v_lshlrev_b64 v[66:67], 12, v[74:75]
	s_ashr_i32 s25, s24, 31
	v_lshl_add_u64 v[66:67], s[72:73], 0, v[66:67]
	v_mov_b64_e32 v[68:69], s[24:25]
	s_or_b64 exec, exec, s[28:29]
	v_lshl_add_u64 v[68:69], v[68:69], 2, s[36:37]
	v_lshl_add_u64 v[84:85], v[68:69], 0, s[14:15]
	v_lshl_add_u64 v[80:81], v[84:85], 0, v[142:143]
	v_lshl_add_u64 v[86:87], v[66:67], 0, v[142:143]
	global_load_dwordx4 v[66:69], v[80:81], off
	global_load_dwordx4 v[70:73], v[86:87], off
	global_load_dwordx4 v[76:79], v[86:87], off offset:16
	s_nop 0
	global_load_dwordx4 v[80:83], v[80:81], off offset:16
	v_lshlrev_b64 v[88:89], 11, v[74:75]
	v_lshl_add_u64 v[88:89], s[26:27], 0, v[88:89]
	v_lshl_add_u64 v[88:89], v[140:141], 1, v[88:89]
	v_lshl_add_u64 v[84:85], v[144:145], 2, v[84:85]
	global_load_dwordx4 v[210:213], v[84:85], off
	global_load_dwordx4 v[214:217], v[86:87], off offset:512
	global_load_dwordx4 v[218:221], v[86:87], off offset:528
	global_load_dwordx4 v[222:225], v[84:85], off offset:16
	s_waitcnt vmcnt(6)
	v_pk_fma_f32 v[64:65], v[64:65], v[68:69], v[72:73]
	v_pk_fma_f32 v[62:63], v[62:63], v[66:67], v[70:71]
	s_waitcnt vmcnt(4)
	v_pk_fma_f32 v[66:67], v[60:61], v[82:83], v[78:79]
	v_pk_fma_f32 v[60:61], v[58:59], v[80:81], v[76:77]
	v_cvt_pk_bf16_f32 v58, v62, v63
	v_cvt_pk_bf16_f32 v59, v64, v65
	v_cvt_pk_bf16_f32 v60, v60, v61
	v_cvt_pk_bf16_f32 v61, v66, v67
	global_store_dwordx4 v[88:89], v[58:61], off
	s_nop 0
	v_or_b32_e32 v58, 16, v74
	v_cmp_lt_i32_e32 vcc, s48, v58
	s_waitcnt vmcnt(3)
	v_pk_fma_f32 v[56:57], v[56:57], v[212:213], v[216:217]
	v_pk_fma_f32 v[54:55], v[54:55], v[210:211], v[214:215]
	s_waitcnt vmcnt(1)
	v_pk_fma_f32 v[60:61], v[52:53], v[224:225], v[220:221]
	v_pk_fma_f32 v[52:53], v[50:51], v[222:223], v[218:219]
	v_cvt_pk_bf16_f32 v50, v54, v55
	v_cvt_pk_bf16_f32 v51, v56, v57
	v_cvt_pk_bf16_f32 v52, v52, v53
	v_cvt_pk_bf16_f32 v53, v60, v61
	global_store_dwordx4 v[88:89], v[50:53], off offset:256
	s_and_saveexec_b64 s[6:7], vcc
	s_xor_b64 s[28:29], exec, s[6:7]
	v_add_u32_e32 v132, 0xffffc010, v74
	v_lshlrev_b64 v[50:51], 12, v[132:133]
	v_lshl_add_u64 v[50:51], s[76:77], 0, v[50:51]
	v_mov_b32_e32 v59, v133
	s_or_saveexec_b64 s[28:29], s[28:29]
	v_mov_b64_e32 v[52:53], 0x6000
	s_xor_b64 exec, exec, s[28:29]
	v_ashrrev_i32_e32 v59, 31, v58
	v_lshlrev_b64 v[50:51], 12, v[58:59]
	s_ashr_i32 s25, s24, 31
	v_lshl_add_u64 v[50:51], s[72:73], 0, v[50:51]
	v_mov_b64_e32 v[52:53], s[24:25]
	s_or_b64 exec, exec, s[28:29]
	v_lshl_add_u64 v[52:53], v[52:53], 2, s[36:37]
	v_lshl_add_u64 v[68:69], v[52:53], 0, s[14:15]
	v_lshl_add_u64 v[64:65], v[68:69], 0, v[142:143]
	v_lshl_add_u64 v[70:71], v[50:51], 0, v[142:143]
	global_load_dwordx4 v[50:53], v[64:65], off
	global_load_dwordx4 v[54:57], v[70:71], off
	global_load_dwordx4 v[60:63], v[70:71], off offset:16
	s_nop 0
	global_load_dwordx4 v[64:67], v[64:65], off offset:16
	v_lshlrev_b64 v[58:59], 11, v[58:59]
	v_lshl_add_u64 v[58:59], s[26:27], 0, v[58:59]
	v_lshl_add_u64 v[72:73], v[140:141], 1, v[58:59]
	v_lshl_add_u64 v[58:59], v[144:145], 2, v[68:69]
	global_load_dwordx4 v[210:213], v[58:59], off
	global_load_dwordx4 v[214:217], v[70:71], off offset:512
	global_load_dwordx4 v[218:221], v[70:71], off offset:528
	global_load_dwordx4 v[222:225], v[58:59], off offset:16
	s_waitcnt vmcnt(6)
	v_pk_fma_f32 v[48:49], v[48:49], v[52:53], v[56:57]
	v_pk_fma_f32 v[46:47], v[46:47], v[50:51], v[54:55]
	s_waitcnt vmcnt(4)
	v_pk_fma_f32 v[50:51], v[44:45], v[66:67], v[62:63]
	v_pk_fma_f32 v[44:45], v[42:43], v[64:65], v[60:61]
	v_cvt_pk_bf16_f32 v42, v46, v47
	v_cvt_pk_bf16_f32 v43, v48, v49
	v_cvt_pk_bf16_f32 v44, v44, v45
	v_cvt_pk_bf16_f32 v45, v50, v51
	global_store_dwordx4 v[72:73], v[42:45], off
	s_nop 0
	s_nop 0
	v_or_b32_e32 v42, 32, v74
	v_cmp_lt_i32_e32 vcc, s48, v42
	s_waitcnt vmcnt(3)
	v_pk_fma_f32 v[40:41], v[40:41], v[212:213], v[216:217]
	v_pk_fma_f32 v[38:39], v[38:39], v[210:211], v[214:215]
	s_waitcnt vmcnt(1)
	v_pk_fma_f32 v[44:45], v[36:37], v[224:225], v[220:221]
	v_pk_fma_f32 v[36:37], v[34:35], v[222:223], v[218:219]
	v_cvt_pk_bf16_f32 v34, v38, v39
	v_cvt_pk_bf16_f32 v35, v40, v41
	v_cvt_pk_bf16_f32 v36, v36, v37
	v_cvt_pk_bf16_f32 v37, v44, v45
	global_store_dwordx4 v[72:73], v[34:37], off offset:256
	s_and_saveexec_b64 s[6:7], vcc
	s_xor_b64 s[28:29], exec, s[6:7]
	v_add_u32_e32 v132, 0xffffc020, v74
	v_lshlrev_b64 v[34:35], 12, v[132:133]
	v_lshl_add_u64 v[34:35], s[76:77], 0, v[34:35]
	v_mov_b32_e32 v43, v133
	s_or_saveexec_b64 s[28:29], s[28:29]
	v_mov_b64_e32 v[36:37], 0x6000
	s_xor_b64 exec, exec, s[28:29]
	v_ashrrev_i32_e32 v43, 31, v42
	v_lshlrev_b64 v[34:35], 12, v[42:43]
	s_ashr_i32 s25, s24, 31
	v_lshl_add_u64 v[34:35], s[72:73], 0, v[34:35]
	v_mov_b64_e32 v[36:37], s[24:25]
	s_or_b64 exec, exec, s[28:29]
	v_lshl_add_u64 v[36:37], v[36:37], 2, s[36:37]
	v_lshl_add_u64 v[52:53], v[36:37], 0, s[14:15]
	v_lshl_add_u64 v[48:49], v[52:53], 0, v[142:143]
	v_lshl_add_u64 v[54:55], v[34:35], 0, v[142:143]
	global_load_dwordx4 v[34:37], v[48:49], off
	global_load_dwordx4 v[38:41], v[54:55], off
	global_load_dwordx4 v[44:47], v[54:55], off offset:16
	s_nop 0
	global_load_dwordx4 v[48:51], v[48:49], off offset:16
	v_lshlrev_b64 v[42:43], 11, v[42:43]
	v_lshl_add_u64 v[42:43], s[26:27], 0, v[42:43]
	v_lshl_add_u64 v[56:57], v[140:141], 1, v[42:43]
	v_lshl_add_u64 v[42:43], v[144:145], 2, v[52:53]
	global_load_dwordx4 v[210:213], v[42:43], off
	global_load_dwordx4 v[214:217], v[54:55], off offset:512
	global_load_dwordx4 v[218:221], v[54:55], off offset:528
	global_load_dwordx4 v[222:225], v[42:43], off offset:16
	s_waitcnt vmcnt(6)
	v_pk_fma_f32 v[32:33], v[32:33], v[36:37], v[40:41]
	v_pk_fma_f32 v[30:31], v[30:31], v[34:35], v[38:39]
	s_waitcnt vmcnt(4)
	v_pk_fma_f32 v[34:35], v[28:29], v[50:51], v[46:47]
	v_pk_fma_f32 v[28:29], v[26:27], v[48:49], v[44:45]
	v_cvt_pk_bf16_f32 v26, v30, v31
	v_cvt_pk_bf16_f32 v27, v32, v33
	v_cvt_pk_bf16_f32 v28, v28, v29
	v_cvt_pk_bf16_f32 v29, v34, v35
	global_store_dwordx4 v[56:57], v[26:29], off
	s_nop 0
	s_nop 0
	v_or_b32_e32 v26, 48, v74
	v_cmp_lt_i32_e32 vcc, s48, v26
	s_waitcnt vmcnt(3)
	v_pk_fma_f32 v[24:25], v[24:25], v[212:213], v[216:217]
	v_pk_fma_f32 v[22:23], v[22:23], v[210:211], v[214:215]
	s_waitcnt vmcnt(1)
	v_pk_fma_f32 v[28:29], v[20:21], v[224:225], v[220:221]
	v_pk_fma_f32 v[20:21], v[18:19], v[222:223], v[218:219]
	v_cvt_pk_bf16_f32 v18, v22, v23
	v_cvt_pk_bf16_f32 v19, v24, v25
	v_cvt_pk_bf16_f32 v20, v20, v21
	v_cvt_pk_bf16_f32 v21, v28, v29
	global_store_dwordx4 v[56:57], v[18:21], off offset:256
	s_and_saveexec_b64 s[6:7], vcc
	s_xor_b64 s[28:29], exec, s[6:7]
	v_add_u32_e32 v132, 0xffffc030, v74
	v_lshlrev_b64 v[18:19], 12, v[132:133]
	v_lshl_add_u64 v[18:19], s[76:77], 0, v[18:19]
	v_mov_b32_e32 v27, v133
	s_or_saveexec_b64 s[28:29], s[28:29]
	v_mov_b64_e32 v[20:21], 0x6000
	s_xor_b64 exec, exec, s[28:29]
	v_ashrrev_i32_e32 v27, 31, v26
	v_lshlrev_b64 v[18:19], 12, v[26:27]
	s_ashr_i32 s25, s24, 31
	v_lshl_add_u64 v[18:19], s[72:73], 0, v[18:19]
	v_mov_b64_e32 v[20:21], s[24:25]
	s_or_b64 exec, exec, s[28:29]
	v_lshl_add_u64 v[20:21], v[20:21], 2, s[36:37]
	v_lshl_add_u64 v[36:37], v[20:21], 0, s[14:15]
	v_lshl_add_u64 v[32:33], v[36:37], 0, v[142:143]
	v_lshl_add_u64 v[38:39], v[18:19], 0, v[142:143]
	global_load_dwordx4 v[18:21], v[32:33], off
	global_load_dwordx4 v[22:25], v[38:39], off
	global_load_dwordx4 v[28:31], v[38:39], off offset:16
	s_nop 0
	global_load_dwordx4 v[32:35], v[32:33], off offset:16
	v_lshlrev_b64 v[26:27], 11, v[26:27]
	v_lshl_add_u64 v[26:27], s[26:27], 0, v[26:27]
	v_lshl_add_u64 v[26:27], v[140:141], 1, v[26:27]
	v_lshl_add_u64 v[36:37], v[144:145], 2, v[36:37]
	s_andn2_b64 vcc, exec, s[4:5]
	s_mov_b64 s[4:5], -1
	global_load_dwordx4 v[210:213], v[36:37], off
	global_load_dwordx4 v[214:217], v[38:39], off offset:512
	global_load_dwordx4 v[218:221], v[38:39], off offset:528
	global_load_dwordx4 v[222:225], v[36:37], off offset:16
	s_waitcnt vmcnt(6)
	v_pk_fma_f32 v[16:17], v[16:17], v[20:21], v[24:25]
	v_pk_fma_f32 v[14:15], v[14:15], v[18:19], v[22:23]
	s_waitcnt vmcnt(4)
	v_pk_fma_f32 v[18:19], v[12:13], v[34:35], v[30:31]
	v_pk_fma_f32 v[12:13], v[10:11], v[32:33], v[28:29]
	v_cvt_pk_bf16_f32 v10, v14, v15
	v_cvt_pk_bf16_f32 v11, v16, v17
	v_cvt_pk_bf16_f32 v12, v12, v13
	v_cvt_pk_bf16_f32 v13, v18, v19
	global_store_dwordx4 v[26:27], v[10:13], off
	s_nop 0
	s_waitcnt vmcnt(3)
	v_pk_fma_f32 v[8:9], v[8:9], v[212:213], v[216:217]
	v_pk_fma_f32 v[6:7], v[6:7], v[210:211], v[214:215]
	s_waitcnt vmcnt(1)
	v_pk_fma_f32 v[10:11], v[4:5], v[224:225], v[220:221]
	v_pk_fma_f32 v[4:5], v[2:3], v[222:223], v[218:219]
	v_cvt_pk_bf16_f32 v2, v6, v7
	v_cvt_pk_bf16_f32 v3, v8, v9
	v_cvt_pk_bf16_f32 v4, v4, v5
	v_cvt_pk_bf16_f32 v5, v10, v11
	global_store_dwordx4 v[26:27], v[2:5], off offset:256
	s_cbranch_vccnz .LBB0_488
	s_andn2_b64 vcc, exec, s[8:9]
	s_cbranch_vccnz .LBB0_487
	s_barrier
	s_branch .LBB0_487
